# scan: wave 0 gate loads issued early with the K/V loads, SCAN_SCALARS waits only for them; prefix scans by DPP instead of 12 ds_bpermute round trips
# speedup vs baseline: 1.0086x; 1.0025x over previous
.LBB0_628:
	s_bitcmp1_b32 s57, 0
	s_cselect_b32 s50, 0x900, 0
	s_add_i32 s61, s50, 0
	s_add_i32 s61, s61, 0x1c800
	s_waitcnt vmcnt(8)
	ds_write_b128 v184, v[4:7]
	s_waitcnt vmcnt(7)
	ds_write_b128 v185, v[8:11]
	s_waitcnt vmcnt(6)
	ds_write_b128 v186, v[12:15]
	s_waitcnt vmcnt(5)
	ds_write_b128 v187, v[16:19]
	s_waitcnt vmcnt(4)
	ds_write_b128 v188, v[20:23]
	s_waitcnt vmcnt(3)
	ds_write_b128 v189, v[24:27]
	s_waitcnt vmcnt(2)
	ds_write_b128 v190, v[28:31]
	s_waitcnt vmcnt(1)
	ds_write_b128 v191, v[32:35]
	v_lshl_add_u32 v1, v160, 2, s61
	ds_read_b32 v2, v1 offset:1536
	s_waitcnt vmcnt(0)
	v_lshlrev_b32_e32 v96, 16, v36
	v_and_b32_e32 v97, 0xffff0000, v36
	ds_write_b16 v165, v36
	ds_write_b16_d16_hi v165, v36 offset:272
	ds_write_b16 v165, v37 offset:544
	ds_write_b16_d16_hi v165, v37 offset:816
	ds_write_b16 v165, v38 offset:1088
	ds_write_b16_d16_hi v165, v38 offset:1360
	ds_write_b16 v165, v39 offset:1632
	ds_write_b16_d16_hi v165, v39 offset:1904
	s_waitcnt lgkmcnt(8)
	v_pk_mul_f32 v[96:97], v[2:3], v[96:97] op_sel_hi:[0,1]
	v_cvt_pk_bf16_f32 v1, v96, v97
	v_lshlrev_b32_e32 v96, 16, v37
	v_and_b32_e32 v97, 0xffff0000, v37
	v_pk_mul_f32 v[96:97], v[2:3], v[96:97] op_sel_hi:[0,1]
	v_cvt_pk_bf16_f32 v3, v96, v97
	v_lshlrev_b32_e32 v96, 16, v38
	v_and_b32_e32 v97, 0xffff0000, v38
	v_pk_mul_f32 v[96:97], v[2:3], v[96:97] op_sel_hi:[0,1]
	v_cvt_pk_bf16_f32 v98, v96, v97
	v_lshlrev_b32_e32 v96, 16, v39
	v_and_b32_e32 v97, 0xffff0000, v39
	v_pk_mul_f32 v[96:97], v[2:3], v[96:97] op_sel_hi:[0,1]
	v_cvt_pk_bf16_f32 v96, v96, v97
	ds_write_b16 v166, v1
	ds_write_b16_d16_hi v166, v1 offset:272
	ds_write_b16 v166, v3 offset:544
	ds_write_b16_d16_hi v166, v3 offset:816
	ds_write_b16 v166, v98 offset:1088
	ds_write_b16_d16_hi v166, v98 offset:1360
	ds_write_b16 v166, v96 offset:1632
	ds_write_b16_d16_hi v166, v96 offset:1904
	s_and_saveexec_b64 s[50:51], s[14:15]
	v_cvt_pk_bf16_f32 v1, v2, s0
	ds_write_b16 v167, v1
	s_or_b64 exec, exec, s[50:51]
	s_cmp_lt_u32 s57, 2
	s_waitcnt lgkmcnt(0)
	s_barrier
	s_cbranch_scc1 .LBB0_655
	s_mov_b32 s99, 0
	s_cmp_eq_u32 s57, 33
	s_cbranch_scc1 .Lscan_kv_early_done
	s_add_i32 s98, s57, -1
	s_and_b64 vcc, s[46:47], exec
	s_cselect_b32 s98, s98, s60
	s_lshl_b32 s98, s98, 7
	s_add_i32 s98, s98, s58
	v_add_u32_e32 v2, s98, v197
	v_add_u32_e32 v4, s98, v198
	v_ashrrev_i32_e32 v3, 31, v2
	v_ashrrev_i32_e32 v5, 31, v4
	v_lshlrev_b64 v[2:3], 11, v[2:3]
	v_lshlrev_b64 v[4:5], 11, v[4:5]
	v_lshl_add_u64 v[2:3], v[148:149], 0, v[2:3]
	v_lshl_add_u64 v[8:9], v[148:149], 0, v[4:5]
	global_load_dwordx4 v[4:7], v[2:3], off
	s_nop 0
	global_load_dwordx4 v[8:11], v[8:9], off
	v_add_u32_e32 v2, s98, v199
	v_add_u32_e32 v12, s98, v200
	v_ashrrev_i32_e32 v3, 31, v2
	v_ashrrev_i32_e32 v13, 31, v12
	v_lshlrev_b64 v[2:3], 11, v[2:3]
	v_lshlrev_b64 v[12:13], 11, v[12:13]
	v_lshl_add_u64 v[2:3], v[148:149], 0, v[2:3]
	v_lshl_add_u64 v[16:17], v[148:149], 0, v[12:13]
	global_load_dwordx4 v[12:15], v[2:3], off
	s_nop 0
	global_load_dwordx4 v[16:19], v[16:17], off
	v_add_u32_e32 v2, s98, v201
	v_add_u32_e32 v20, s98, v202
	v_ashrrev_i32_e32 v3, 31, v2
	v_ashrrev_i32_e32 v21, 31, v20
	v_lshlrev_b64 v[2:3], 11, v[2:3]
	v_lshlrev_b64 v[20:21], 11, v[20:21]
	v_lshl_add_u64 v[2:3], v[148:149], 0, v[2:3]
	v_lshl_add_u64 v[24:25], v[148:149], 0, v[20:21]
	global_load_dwordx4 v[20:23], v[2:3], off
	s_nop 0
	global_load_dwordx4 v[24:27], v[24:25], off
	v_add_u32_e32 v2, s98, v203
	v_add_u32_e32 v28, s98, v204
	v_ashrrev_i32_e32 v3, 31, v2
	v_ashrrev_i32_e32 v29, 31, v28
	v_lshlrev_b64 v[2:3], 11, v[2:3]
	v_lshlrev_b64 v[28:29], 11, v[28:29]
	v_lshl_add_u64 v[2:3], v[148:149], 0, v[2:3]
	v_lshl_add_u64 v[32:33], v[148:149], 0, v[28:29]
	global_load_dwordx4 v[28:31], v[2:3], off
	s_nop 0
	global_load_dwordx4 v[32:35], v[32:33], off
	v_or_b32_e32 v2, s98, v205
	v_ashrrev_i32_e32 v3, 31, v2
	v_lshlrev_b64 v[2:3], 11, v[2:3]
	v_lshl_add_u64 v[2:3], v[154:155], 0, v[2:3]
	global_load_dwordx4 v[36:39], v[2:3], off
	s_and_saveexec_b64 vcc, s[10:11]
	s_cbranch_execz .Lscan_g_early
	v_or_b32_e32 v2, s98, v206
	v_ashrrev_i32_e32 v3, 31, v2
	v_or_b32_e32 v96, s98, v207
	v_lshlrev_b64 v[2:3], 6, v[2:3]
	v_ashrrev_i32_e32 v97, 31, v96
	v_lshl_add_u64 v[2:3], s[52:53], 0, v[2:3]
	v_lshlrev_b64 v[96:97], 6, v[96:97]
	v_lshl_add_u64 v[96:97], s[52:53], 0, v[96:97]
	global_load_dword v150, v[2:3], off
	global_load_dword v208, v[2:3], off offset:16
	global_load_dword v151, v[96:97], off
	global_load_dword v209, v[96:97], off offset:16
.Lscan_g_early:
	s_or_b64 exec, exec, vcc
	s_mov_b32 s99, 1

.LBB0_656:
	v_sub_co_u32_e64 v1, s[54:55], s57, 1
	s_and_b64 s[62:63], s[46:47], exec
	v_readfirstlane_b32 s62, v1
	s_cselect_b32 s62, s62, s60
	s_lshl_b32 s62, s62, 7
	s_add_i32 s62, s62, s58
	s_and_b64 vcc, s[54:55], exec
	s_cselect_b32 s63, s59, s62
	s_cmp_eq_u32 s99, 1
	s_cbranch_scc1 .Lscan_kv_late_skip
	v_add_u32_e32 v2, s63, v197
	v_add_u32_e32 v4, s63, v198
	v_ashrrev_i32_e32 v3, 31, v2
	v_ashrrev_i32_e32 v5, 31, v4
	v_lshlrev_b64 v[2:3], 11, v[2:3]
	v_lshlrev_b64 v[4:5], 11, v[4:5]
	v_lshl_add_u64 v[2:3], v[148:149], 0, v[2:3]
	v_lshl_add_u64 v[8:9], v[148:149], 0, v[4:5]
	global_load_dwordx4 v[4:7], v[2:3], off
	s_nop 0
	global_load_dwordx4 v[8:11], v[8:9], off
	v_add_u32_e32 v2, s63, v199
	v_add_u32_e32 v12, s63, v200
	v_ashrrev_i32_e32 v3, 31, v2
	v_ashrrev_i32_e32 v13, 31, v12
	v_lshlrev_b64 v[2:3], 11, v[2:3]
	v_lshlrev_b64 v[12:13], 11, v[12:13]
	v_lshl_add_u64 v[2:3], v[148:149], 0, v[2:3]
	v_lshl_add_u64 v[16:17], v[148:149], 0, v[12:13]
	global_load_dwordx4 v[12:15], v[2:3], off
	s_nop 0
	global_load_dwordx4 v[16:19], v[16:17], off
	v_add_u32_e32 v2, s63, v201
	v_add_u32_e32 v20, s63, v202
	v_ashrrev_i32_e32 v3, 31, v2
	v_ashrrev_i32_e32 v21, 31, v20
	v_lshlrev_b64 v[2:3], 11, v[2:3]
	v_lshlrev_b64 v[20:21], 11, v[20:21]
	v_lshl_add_u64 v[2:3], v[148:149], 0, v[2:3]
	v_lshl_add_u64 v[24:25], v[148:149], 0, v[20:21]
	global_load_dwordx4 v[20:23], v[2:3], off
	s_nop 0
	global_load_dwordx4 v[24:27], v[24:25], off
	v_add_u32_e32 v2, s63, v203
	v_add_u32_e32 v28, s63, v204
	v_ashrrev_i32_e32 v3, 31, v2
	v_ashrrev_i32_e32 v29, 31, v28
	v_lshlrev_b64 v[2:3], 11, v[2:3]
	v_lshlrev_b64 v[28:29], 11, v[28:29]
	v_lshl_add_u64 v[2:3], v[148:149], 0, v[2:3]
	v_lshl_add_u64 v[32:33], v[148:149], 0, v[28:29]
	global_load_dwordx4 v[28:31], v[2:3], off
	s_nop 0
	global_load_dwordx4 v[32:35], v[32:33], off
	v_or_b32_e32 v2, s63, v205
	v_ashrrev_i32_e32 v3, 31, v2
	v_lshlrev_b64 v[2:3], 11, v[2:3]
	v_lshl_add_u64 v[2:3], v[154:155], 0, v[2:3]
	global_load_dwordx4 v[36:39], v[2:3], off
	s_and_saveexec_b64 vcc, s[10:11]
	s_cbranch_execz .LBB0_658
	v_or_b32_e32 v2, s63, v206
	v_ashrrev_i32_e32 v3, 31, v2
	v_or_b32_e32 v96, s63, v207
	v_lshlrev_b64 v[2:3], 6, v[2:3]
	v_ashrrev_i32_e32 v97, 31, v96
	v_lshl_add_u64 v[2:3], s[52:53], 0, v[2:3]
	v_lshlrev_b64 v[96:97], 6, v[96:97]
	v_lshl_add_u64 v[96:97], s[52:53], 0, v[96:97]
	global_load_dword v150, v[2:3], off
	global_load_dword v208, v[2:3], off offset:16
	global_load_dword v151, v[96:97], off
	global_load_dword v209, v[96:97], off offset:16

.Lscan_kv_late_skip:
	s_xor_b64 s[54:55], s[54:55], -1
	s_andn2_b64 vcc, exec, s[54:55]
	s_cbranch_vccnz .LBB0_660
	v_add_u32_e32 v2, s62, v145
	v_ashrrev_i32_e32 v3, 31, v2
	v_lshlrev_b64 v[2:3], 11, v[2:3]
	v_lshl_add_u64 v[2:3], v[158:159], 0, v[2:3]
	global_load_dwordx4 v[40:43], v[2:3], off
	global_load_dwordx4 v[44:47], v[2:3], off offset:64
	global_load_dwordx4 v[48:51], v[2:3], off offset:128
	global_load_dwordx4 v[52:55], v[2:3], off offset:192
	global_load_dwordx4 v[56:59], v[2:3], off offset:256
	global_load_dwordx4 v[60:63], v[2:3], off offset:320
	global_load_dwordx4 v[64:67], v[2:3], off offset:384
	global_load_dwordx4 v[68:71], v[2:3], off offset:448

.LBB0_679:
	s_cmp_eq_u32 s99, 1
	s_cbranch_scc1 .Lscan_g_wait
	s_waitcnt vmcnt(0)
.Lscan_g_wait:
	s_waitcnt vmcnt(10)
	s_mov_b32 s50, 0xbfb8aa3b
	v_mul_f32_e64 v1, |v208|, s50
	v_exp_f32_e32 v1, v1
	s_mov_b32 s62, 0x800000
	v_max_f32_e32 v2, v208, v208
	v_mul_f32_e64 v96, |v209|, s50
	v_add_f32_e32 v1, 1.0, v1
	v_cmp_gt_f32_e32 vcc, s62, v1
	s_mov_b32 s63, 0x3f317217
	s_mov_b32 s64, 0x7f800000
	v_cndmask_b32_e64 v3, 0, 32, vcc
	v_ldexp_f32 v1, v1, v3
	v_log_f32_e32 v1, v1
	v_min_f32_e32 v3, 0, v2
	v_exp_f32_e32 v2, v96
	s_bitcmp1_b32 s57, 0
	v_mul_f32_e32 v96, 0x3f317217, v1
	v_fma_f32 v96, v1, s63, -v96
	v_fmac_f32_e32 v96, 0x3377d1cf, v1
	v_fmac_f32_e32 v96, 0x3f317217, v1
	v_cmp_lt_f32_e64 s[50:51], |v1|, s64
	v_add_f32_e32 v2, 1.0, v2
	s_nop 0
	v_cndmask_b32_e64 v1, v1, v96, s[50:51]
	v_cndmask_b32_e32 v96, 0, v231, vcc
	v_cmp_gt_f32_e32 vcc, s62, v2
	s_nop 1
	v_cndmask_b32_e64 v97, 0, 32, vcc
	v_ldexp_f32 v2, v2, v97
	v_log_f32_e32 v98, v2
	v_sub_f32_e32 v97, v1, v96
	v_max_f32_e32 v1, v209, v209
	v_min_f32_e32 v2, 0, v1
	v_mul_f32_e32 v1, 0x3f317217, v98
	v_fma_f32 v1, v98, s63, -v1
	v_fmac_f32_e32 v1, 0x3377d1cf, v98
	v_fmac_f32_e32 v1, 0x3f317217, v98
	v_cmp_lt_f32_e64 s[50:51], |v98|, s64
	v_cndmask_b32_e32 v96, 0, v231, vcc
	s_nop 0
	v_cndmask_b32_e64 v1, v98, v1, s[50:51]
	v_sub_f32_e32 v96, v1, v96
	v_pk_add_f32 v[2:3], v[2:3], v[96:97] neg_lo:[0,1] neg_hi:[0,1]
	v_add_u32_e32 v96, -1, v230
	v_add_f32_e32 v1, v2, v3
	v_and_b32_e32 v3, 64, v230
	v_cmp_lt_i32_e32 vcc, v96, v3
	s_cselect_b32 s50, 0x900, 0
	s_add_i32 s62, s50, 0
	v_cndmask_b32_e32 v96, v96, v230, vcc
	v_lshlrev_b32_e32 v100, 2, v96
	s_add_i32 s62, s62, 0x1c800
	v_lshl_add_u32 v105, v162, 2, s62
	s_nop 1
	v_add_f32_dpp v1, v1, v1 row_shr:1 row_mask:0xf bank_mask:0xf
	s_nop 1
	v_add_f32_dpp v1, v1, v1 row_shr:2 row_mask:0xf bank_mask:0xf
	s_nop 1
	v_add_f32_dpp v1, v1, v1 row_shr:4 row_mask:0xf bank_mask:0xf
	s_nop 1
	v_add_f32_dpp v1, v1, v1 row_shr:8 row_mask:0xf bank_mask:0xf
	s_nop 1
	v_add_f32_dpp v1, v1, v1 row_bcast:15 row_mask:0xa bank_mask:0xf
	s_nop 1
	v_add_f32_dpp v1, v1, v1 row_bcast:31 row_mask:0xc bank_mask:0xf
	v_mov_b32_e32 v97, v1
	v_sub_f32_e32 v96, v1, v2
	v_pk_add_f32 v[98:99], v[150:151], v[96:97] neg_lo:[0,1] neg_hi:[0,1]
	s_nop 0
	v_max_f32_e32 v1, v98, v99
	s_nop 1
	v_max_f32_dpp v1, v1, v1 row_shr:1 row_mask:0xf bank_mask:0xf
	s_nop 1
	v_max_f32_dpp v1, v1, v1 row_shr:2 row_mask:0xf bank_mask:0xf
	s_nop 1
	v_max_f32_dpp v1, v1, v1 row_shr:4 row_mask:0xf bank_mask:0xf
	s_nop 1
	v_max_f32_dpp v1, v1, v1 row_shr:8 row_mask:0xf bank_mask:0xf
	s_nop 1
	v_max_f32_dpp v1, v1, v1 row_bcast:15 row_mask:0xa bank_mask:0xf
	s_nop 1
	v_max_f32_dpp v1, v1, v1 row_bcast:31 row_mask:0xc bank_mask:0xf
	v_lshl_or_b32 v101, v230, 2, v232
	v_max_f32_e32 v3, v153, v153
	v_mov_b32_e32 v104, v1
	ds_bpermute_b32 v2, v100, v104
	ds_bpermute_b32 v100, v101, v104
	ds_bpermute_b32 v1, v101, v97
	s_waitcnt lgkmcnt(2)
	v_cndmask_b32_e64 v101, v2, v233, s[12:13]
	s_waitcnt lgkmcnt(1)
	v_max_f32_e32 v2, v100, v100
	v_max_f32_e32 v2, v3, v2
	v_max3_f32 v100, v101, v98, v153
	v_sub_f32_e32 v101, v98, v2
	v_mul_f32_e32 v101, 0x3fb8aa3b, v101
	v_exp_f32_e32 v102, v101
	v_sub_f32_e32 v101, v99, v2
	v_mul_f32_e32 v101, 0x3fb8aa3b, v101
	v_exp_f32_e32 v103, v101
	v_max_f32_e32 v101, v104, v104
	v_max_f32_e32 v101, v101, v3
	ds_write2st64_b64 v105, v[98:99], v[100:101] offset1:1
	ds_write2st64_b64 v105, v[96:97], v[102:103] offset0:2 offset1:3
	s_and_saveexec_b64 s[50:51], s[12:13]
	s_cbranch_execz .LBB0_622
	v_sub_f32_e32 v3, v153, v2
	v_mul_f32_e32 v3, 0x3fb8aa3b, v3
	v_exp_f32_e32 v152, v3
	v_mov_b32_e32 v3, s62
	ds_write_b64 v3, v[152:153] offset:2048
	s_branch .LBB0_622
